# adds: sample-row skinny GEMM tails restructured (weights prefetched before A-fill in P6; gain loads batched in P1; WG0 copy + last-WG norm tails de-serialized)
# speedup vs baseline: 1.0161x; 1.0116x over previous
.LBB0_545:
	v_readlane_b32 s56, v254, 9
	v_readlane_b32 s57, v254, 10
	s_mov_b32 s85, 0
	v_readlane_b32 s58, v254, 11
	v_readlane_b32 s59, v254, 12
	s_mov_b64 s[12:13], s[56:57]
	s_lshl_b64 s[0:1], s[84:85], 13
	s_mov_b64 s[14:15], s[58:59]
	s_add_u32 s0, s14, s0
	s_addc_u32 s1, s15, s1
	v_lshlrev_b32_e32 v40, 4, v212
	global_load_dwordx4 v[30:33], v40, s[0:1]
	global_load_dwordx4 v[26:29], v40, s[0:1] offset:1024
	global_load_dwordx4 v[22:25], v40, s[0:1] offset:2048
	global_load_dwordx4 v[18:21], v40, s[0:1] offset:3072
	v_mov_b32_e32 v41, 0
	s_movk_i32 s2, 0x1000
	s_waitcnt vmcnt(15)
	v_lshl_add_u64 v[2:3], s[0:1], 0, v[40:41]
	s_waitcnt vmcnt(14)
	v_add_co_u32_e32 v6, vcc, s2, v2
	v_mbcnt_lo_u32_b32 v35, -1, 0
	s_nop 0
	v_addc_co_u32_e32 v7, vcc, 0, v3, vcc
	global_load_dwordx4 v[14:17], v[6:7], off
	global_load_dwordx4 v[10:13], v[6:7], off offset:1024
	global_load_dwordx4 v[2:5], v[6:7], off offset:3072
	s_nop 0
	global_load_dwordx4 v[6:9], v[6:7], off offset:2048
	v_mbcnt_hi_u32_b32 v35, -1, v35
	v_and_b32_e32 v36, 64, v35
	v_xor_b32_e32 v37, 1, v35
	v_add_u32_e32 v58, 64, v36
	v_cmp_lt_i32_e32 vcc, v37, v58
	v_readlane_b32 s0, v254, 25
	v_readlane_b32 s2, v254, 27
	v_cndmask_b32_e32 v36, v35, v37, vcc
	v_lshlrev_b32_e32 v59, 2, v36
	v_readlane_b32 s3, v254, 28
	v_readlane_b32 s12, v254, 37
	v_readlane_b32 s13, v254, 38
	v_readlane_b32 s14, v254, 39
	v_readlane_b32 s15, v254, 40
	v_readlane_b32 s1, v254, 26
	s_mov_b64 s[14:15], s[2:3]
	v_lshl_add_u64 v[42:43], s[14:15], 0, v[40:41]
	v_xor_b32_e32 v41, 2, v35
	v_cmp_lt_i32_e32 vcc, v41, v58
	s_cmp_lg_u64 s[14:15], 0
	v_mov_b32_e32 v34, 1.0
	s_mov_b64 s[12:13], s[0:1]
	s_cselect_b64 s[2:3], -1, 0
	s_cmp_eq_u64 s[14:15], 0
	v_readlane_b32 s60, v254, 13
	v_readlane_b32 s61, v254, 14
	v_readlane_b32 s62, v254, 15
	v_readlane_b32 s63, v254, 16
	v_readlane_b32 s64, v254, 17
	v_readlane_b32 s65, v254, 18
	v_readlane_b32 s66, v254, 19
	v_readlane_b32 s67, v254, 20
	v_readlane_b32 s68, v254, 21
	v_readlane_b32 s69, v254, 22
	v_readlane_b32 s70, v254, 23
	v_readlane_b32 s71, v254, 24
	v_readlane_b32 s4, v254, 29
	v_readlane_b32 s5, v254, 30
	v_readlane_b32 s6, v254, 31
	v_readlane_b32 s7, v254, 32
	v_readlane_b32 s8, v254, 33
	v_readlane_b32 s9, v254, 34
	v_readlane_b32 s10, v254, 35
	v_readlane_b32 s11, v254, 36
	s_waitcnt vmcnt(7)
	v_mov_b32_e32 v38, v31
	s_waitcnt vmcnt(6)
	v_mov_b32_e32 v39, v27
	v_mov_b32_e32 v46, v33
	v_mov_b32_e32 v47, v29
	v_mov_b32_e32 v36, v30
	v_mov_b32_e32 v37, v26
	v_mov_b32_e32 v44, v32
	v_mov_b32_e32 v45, v28
	s_waitcnt vmcnt(5)
	v_pk_mul_f32 v[48:49], v[24:25], v[24:25]
	v_pk_mul_f32 v[50:51], v[22:23], v[22:23]
	v_pk_mul_f32 v[38:39], v[38:39], v[38:39]
	v_pk_mul_f32 v[46:47], v[46:47], v[46:47]
	v_pk_mov_b32 v[56:57], v[50:51], v[48:49] op_sel:[1,0]
	v_mov_b32_e32 v51, v49
	v_pk_fma_f32 v[36:37], v[36:37], v[36:37], v[38:39]
	v_pk_fma_f32 v[38:39], v[44:45], v[44:45], v[46:47]
	s_waitcnt vmcnt(4)
	v_mul_f32_e32 v52, v19, v19
	v_mul_f32_e32 v54, v21, v21
	v_pk_add_f32 v[44:45], v[56:57], v[50:51]
	v_pk_add_f32 v[36:37], v[36:37], v[38:39]
	v_pk_fma_f32 v[48:49], v[18:19], v[18:19], v[52:53] op_sel_hi:[1,1,0]
	v_pk_fma_f32 v[52:53], v[20:21], v[20:21], v[54:55] op_sel_hi:[1,1,0]
	s_waitcnt vmcnt(3)
	v_mul_f32_e32 v57, v14, v14
	v_mul_f32_e32 v60, v15, v15
	v_pk_add_f32 v[38:39], v[44:45], v[44:45] op_sel:[0,1] op_sel_hi:[1,0]
	v_pk_add_f32 v[36:37], v[36:37], v[36:37] op_sel:[0,1] op_sel_hi:[1,0]
	v_mul_f32_e32 v49, v16, v16
	v_mul_f32_e32 v53, v17, v17
	s_waitcnt vmcnt(2)
	v_pk_mul_f32 v[46:47], v[12:13], v[12:13]
	v_pk_mul_f32 v[50:51], v[10:11], v[10:11]
	v_mov_b32_e32 v39, v60
	v_mov_b32_e32 v37, v57
	v_pk_mov_b32 v[44:45], v[50:51], v[46:47] op_sel:[1,0]
	v_mov_b32_e32 v51, v47
	v_pk_add_f32 v[48:49], v[48:49], v[52:53]
	v_pk_add_f32 v[36:37], v[36:37], v[38:39]
	s_waitcnt vmcnt(0)
	v_mul_f32_e32 v54, v7, v7
	v_mul_f32_e32 v56, v9, v9
	v_pk_add_f32 v[44:45], v[44:45], v[50:51]
	v_pk_add_f32 v[36:37], v[36:37], v[48:49]
	v_mul_f32_e32 v61, v2, v2
	v_mul_f32_e32 v62, v3, v3
	v_mul_f32_e32 v63, v4, v4
	v_mul_f32_e32 v64, v5, v5
	v_pk_fma_f32 v[46:47], v[6:7], v[6:7], v[54:55] op_sel_hi:[1,1,0]
	v_pk_fma_f32 v[54:55], v[8:9], v[8:9], v[56:57] op_sel_hi:[1,1,0]
	v_pk_add_f32 v[44:45], v[44:45], v[44:45] op_sel:[0,1] op_sel_hi:[1,0]
	v_pk_add_f32 v[36:37], v[36:37], v[36:37] op_sel:[0,1] op_sel_hi:[1,0]
	v_mov_b32_e32 v47, v63
	v_mov_b32_e32 v55, v64
	v_mov_b32_e32 v45, v62
	v_mov_b32_e32 v37, v61
	v_pk_add_f32 v[46:47], v[46:47], v[54:55]
	v_pk_add_f32 v[36:37], v[36:37], v[44:45]
	v_cndmask_b32_e32 v39, v35, v41, vcc
	v_pk_add_f32 v[36:37], v[36:37], v[46:47]
	v_lshlrev_b32_e32 v39, 2, v39
	v_add_f32_e32 v36, v36, v37
	ds_bpermute_b32 v37, v59, v36
	v_xor_b32_e32 v38, 4, v35
	v_cmp_lt_i32_e32 vcc, v38, v58
	s_waitcnt lgkmcnt(0)
	v_add_f32_e32 v36, v36, v37
	ds_bpermute_b32 v37, v39, v36
	v_cndmask_b32_e32 v38, v35, v38, vcc
	v_lshlrev_b32_e32 v38, 2, v38
	v_xor_b32_e32 v39, 8, v35
	v_cmp_lt_i32_e32 vcc, v39, v58
	s_waitcnt lgkmcnt(0)
	v_add_f32_e32 v36, v36, v37
	ds_bpermute_b32 v37, v38, v36
	v_cndmask_b32_e32 v39, v35, v39, vcc
	v_lshlrev_b32_e32 v39, 2, v39
	v_xor_b32_e32 v38, 16, v35
	v_cmp_lt_i32_e32 vcc, v38, v58
	s_waitcnt lgkmcnt(0)
	v_add_f32_e32 v36, v36, v37
	ds_bpermute_b32 v37, v39, v36
	v_cndmask_b32_e32 v38, v35, v38, vcc
	v_lshlrev_b32_e32 v38, 2, v38
	v_xor_b32_e32 v39, 32, v35
	v_cmp_lt_i32_e32 vcc, v39, v58
	s_waitcnt lgkmcnt(0)
	v_add_f32_e32 v36, v36, v37
	ds_bpermute_b32 v37, v38, v36
	v_cndmask_b32_e32 v35, v35, v39, vcc
	v_lshlrev_b32_e32 v38, 2, v35
	v_mov_b32_e32 v39, 1.0
	s_waitcnt lgkmcnt(0)
	v_add_f32_e32 v35, v36, v37
	ds_bpermute_b32 v41, v38, v35
	v_mov_b32_e32 v36, 1.0
	v_mov_b32_e32 v37, 1.0
	v_mov_b32_e32 v38, 1.0
	s_cbranch_scc1 .Lp1fill_gnull
	global_load_dwordx4 v[36:39], v[42:43], off
	global_load_dwordx4 v[46:49], v[42:43], off offset:1024
	global_load_dwordx4 v[50:53], v[42:43], off offset:2048
	global_load_dwordx4 v[54:57], v[42:43], off offset:3072
	v_add_co_u32_e32 v72, vcc, 0x1000, v42
	s_nop 1
	v_addc_co_u32_e32 v73, vcc, 0, v43, vcc
	global_load_dwordx4 v[58:61], v[72:73], off
	global_load_dwordx4 v[62:65], v[72:73], off offset:1024
	global_load_dwordx4 v[66:69], v[72:73], off offset:2048
	global_load_dwordx4 v[70:73], v[72:73], off offset:3072
	s_branch .LBB0_547
.Lp1fill_gnull:
	v_mov_b32_e32 v46, 1.0
	v_mov_b32_e32 v47, 1.0
	v_mov_b32_e32 v48, 1.0
	v_mov_b32_e32 v49, 1.0
	v_mov_b32_e32 v50, 1.0
	v_mov_b32_e32 v51, 1.0
	v_mov_b32_e32 v52, 1.0
	v_mov_b32_e32 v53, 1.0
	v_mov_b32_e32 v54, 1.0
	v_mov_b32_e32 v55, 1.0
	v_mov_b32_e32 v56, 1.0
	v_mov_b32_e32 v57, 1.0
	v_mov_b32_e32 v58, 1.0
	v_mov_b32_e32 v59, 1.0
	v_mov_b32_e32 v60, 1.0
	v_mov_b32_e32 v61, 1.0
	v_mov_b32_e32 v62, 1.0
	v_mov_b32_e32 v63, 1.0
	v_mov_b32_e32 v64, 1.0
	v_mov_b32_e32 v65, 1.0
	v_mov_b32_e32 v66, 1.0
	v_mov_b32_e32 v67, 1.0
	v_mov_b32_e32 v68, 1.0
	v_mov_b32_e32 v69, 1.0
	v_mov_b32_e32 v70, 1.0
	v_mov_b32_e32 v71, 1.0
	v_mov_b32_e32 v72, 1.0
	v_mov_b32_e32 v73, 1.0
.LBB0_547:
	s_waitcnt lgkmcnt(0)
	v_add_f32_e32 v35, v35, v41
	v_mov_b32_e32 v41, 0x358637bd
	v_fmac_f32_e32 v41, 0x3a000000, v35
	s_mov_b32 s0, 0x800000
	v_mul_f32_e32 v35, 0x4b800000, v41
	v_cmp_gt_f32_e32 vcc, s0, v41
	v_readlane_b32 s0, v254, 62
	s_add_i32 s0, s0, 0
	v_cndmask_b32_e32 v35, v41, v35, vcc
	v_rsq_f32_e32 v35, v35
	s_nop 0
	v_mul_f32_e32 v41, 0x45800000, v35
	v_cndmask_b32_e32 v44, v35, v41, vcc
	v_mov_b32_e32 v45, v44
	v_pk_mul_f32 v[30:31], v[30:31], v[44:45] op_sel_hi:[1,0]
	v_pk_mul_f32 v[32:33], v[32:33], v[44:45] op_sel_hi:[1,0]
	s_waitcnt vmcnt(0)
	v_pk_mul_f32 v[30:31], v[30:31], v[36:37]
	v_pk_mul_f32 v[32:33], v[32:33], v[38:39]
	v_lshl_add_u32 v41, v212, 3, s0
	v_cvt_pk_bf16_f32 v30, v30, v31
	v_cvt_pk_bf16_f32 v31, v32, v33
	ds_write_b64 v41, v[30:31]
	v_pk_mul_f32 v[26:27], v[26:27], v[44:45]
	v_pk_mul_f32 v[28:29], v[28:29], v[44:45]
	v_pk_mul_f32 v[26:27], v[26:27], v[46:47]
	v_pk_mul_f32 v[28:29], v[28:29], v[48:49]
	v_cvt_pk_bf16_f32 v26, v26, v27
	v_cvt_pk_bf16_f32 v27, v28, v29
	ds_write_b64 v41, v[26:27] offset:512
	v_pk_mul_f32 v[22:23], v[22:23], v[44:45]
	v_pk_mul_f32 v[24:25], v[24:25], v[44:45]
	v_pk_mul_f32 v[22:23], v[22:23], v[50:51]
	v_pk_mul_f32 v[24:25], v[24:25], v[52:53]
	v_cvt_pk_bf16_f32 v22, v22, v23
	v_cvt_pk_bf16_f32 v23, v24, v25
	ds_write_b64 v41, v[22:23] offset:1024
	v_pk_mul_f32 v[18:19], v[18:19], v[44:45]
	v_pk_mul_f32 v[20:21], v[20:21], v[44:45]
	v_pk_mul_f32 v[18:19], v[18:19], v[54:55]
	v_pk_mul_f32 v[20:21], v[20:21], v[56:57]
	v_cvt_pk_bf16_f32 v18, v18, v19
	v_cvt_pk_bf16_f32 v19, v20, v21
	ds_write_b64 v41, v[18:19] offset:1536
	v_pk_mul_f32 v[14:15], v[14:15], v[44:45]
	v_pk_mul_f32 v[16:17], v[16:17], v[44:45]
	v_pk_mul_f32 v[14:15], v[14:15], v[58:59]
	v_pk_mul_f32 v[16:17], v[16:17], v[60:61]
	v_cvt_pk_bf16_f32 v14, v14, v15
	v_cvt_pk_bf16_f32 v15, v16, v17
	ds_write_b64 v41, v[14:15] offset:2048
	v_pk_mul_f32 v[10:11], v[10:11], v[44:45]
	v_pk_mul_f32 v[12:13], v[12:13], v[44:45]
	v_pk_mul_f32 v[10:11], v[10:11], v[62:63]
	v_pk_mul_f32 v[12:13], v[12:13], v[64:65]
	v_cvt_pk_bf16_f32 v10, v10, v11
	v_cvt_pk_bf16_f32 v11, v12, v13
	ds_write_b64 v41, v[10:11] offset:2560
	v_pk_mul_f32 v[6:7], v[6:7], v[44:45]
	v_pk_mul_f32 v[8:9], v[8:9], v[44:45]
	v_pk_mul_f32 v[6:7], v[6:7], v[66:67]
	v_pk_mul_f32 v[8:9], v[8:9], v[68:69]
	v_cvt_pk_bf16_f32 v6, v6, v7
	v_cvt_pk_bf16_f32 v7, v8, v9
	ds_write_b64 v41, v[6:7] offset:3072
	v_pk_mul_f32 v[2:3], v[2:3], v[44:45]
	v_pk_mul_f32 v[4:5], v[4:5], v[44:45]
	v_pk_mul_f32 v[2:3], v[2:3], v[70:71]
	v_pk_mul_f32 v[4:5], v[4:5], v[72:73]
	v_cvt_pk_bf16_f32 v2, v2, v3
	v_cvt_pk_bf16_f32 v3, v4, v5
	ds_write_b64 v41, v[2:3] offset:3584
	v_readlane_b32 s0, v254, 3
	s_cmpk_gt_i32 s0, 0x160
	s_waitcnt lgkmcnt(0)
	s_barrier
	s_cbranch_scc1 .LBB0_575
	s_lshl_b32 s2, s84, 9
	s_add_u32 s0, s46, s2
	s_addc_u32 s1, s47, 0
	v_and_b32_e32 v6, 48, v212
	v_mov_b32_e32 v7, 0
	v_lshl_add_u64 v[8:9], s[0:1], 0, v[6:7]
	v_or_b32_e32 v3, s2, v6
	v_and_b32_e32 v6, 0x70, v0
	v_lshlrev_b32_e32 v5, 2, v160
	v_lshlrev_b32_e32 v6, 2, v6
	s_add_i32 s2, s2, 0
	v_and_b32_e32 v2, 7, v0
	s_movk_i32 s0, 0x1040
	v_add3_u32 v10, 0, v6, v5
	v_mul_i32_i24_e32 v6, 0x1620, v1
	v_add_u32_e32 v5, s2, v5
	v_readlane_b32 s2, v254, 2
	v_mad_u32_u24 v2, v2, s0, 0
	v_and_b32_e32 v4, 0x300, v40
	s_movk_i32 s3, 0x80
	v_readlane_b32 s18, v254, 3
	s_lshl_b32 s15, s2, 4
	v_or_b32_e32 v11, v6, v160
	s_movk_i32 s2, 0xede0
	v_cmp_lt_u32_e64 s[0:1], 7, v160
	v_cmp_gt_u32_e64 s[4:5], 32, v212
	v_cmp_gt_u32_e64 s[6:7], s3, v0
	s_lshl_b32 s14, s18, 4
	v_mad_i32_i24 v1, v1, s2, v11
	v_add_u32_e32 v12, v2, v3
	v_add_u32_e32 v13, v5, v4
	s_branch .LBB0_564

.LBB0_1540:
	s_mov_b32 s85, 0
	s_lshl_b64 s[0:1], s[84:85], 13
	s_add_u32 s0, s82, s0
	s_addc_u32 s1, s83, s1
	s_waitcnt vmcnt(4)
	v_lshlrev_b32_e32 v2, 4, v212
	s_waitcnt lgkmcnt(0)
	v_mov_b32_e32 v3, 0
	v_lshl_add_u64 v[28:29], s[0:1], 0, v[2:3]
	s_mov_b64 s[0:1], 0x25850000
	v_lshl_add_u64 v[36:37], v[28:29], 0, s[0:1]
	s_mov_b32 s0, 0x25851000
	v_add_co_u32_e32 v30, vcc, s0, v28
	s_nop 1
	v_addc_co_u32_e32 v31, vcc, 0, v29, vcc
	v_add_co_u32_e32 v38, vcc, 0x25850000, v28
	s_barrier
	s_nop 0
	v_addc_co_u32_e32 v39, vcc, 0, v29, vcc
	v_readlane_b32 s99, v254, 3
	v_and_b32_e32 v142, 15, v0
	s_lshl_b32 s100, s84, 9
	v_and_b32_e32 v144, 48, v212
	v_mov_b32_e32 v145, 0
	s_add_u32 s100, s82, s100
	s_addc_u32 s101, s83, 0
	v_lshl_or_b32 v142, s99, 4, v142
	v_lshl_add_u64 v[144:145], s[100:101], 0, v[144:145]
	s_mov_b64 s[100:101], 0x2200000
	v_ashrrev_i32_e32 v143, 31, v142
	v_lshl_add_u64 v[144:145], v[144:145], 0, s[100:101]
	v_lshlrev_b64 v[146:147], 12, v[142:143]
	v_lshl_add_u64 v[146:147], v[144:145], 0, v[146:147]
	global_load_dwordx4 v[74:77], v[146:147], off
	global_load_dwordx4 v[78:81], v[146:147], off offset:64
	global_load_dwordx4 v[82:85], v[146:147], off offset:128
	global_load_dwordx4 v[86:89], v[146:147], off offset:192
	global_load_dwordx4 v[90:93], v[146:147], off offset:256
	global_load_dwordx4 v[94:97], v[146:147], off offset:320
	global_load_dwordx4 v[98:101], v[146:147], off offset:384
	global_load_dwordx4 v[102:105], v[146:147], off offset:448
	v_readlane_b32 s99, v254, 2
	s_nop 3
	s_lshl_b32 s99, s99, 4
	v_add_u32_e32 v142, s99, v142
	v_ashrrev_i32_e32 v143, 31, v142
	v_lshlrev_b64 v[146:147], 12, v[142:143]
	v_lshl_add_u64 v[146:147], v[144:145], 0, v[146:147]
	global_load_dwordx4 v[106:109], v[146:147], off
	global_load_dwordx4 v[110:113], v[146:147], off offset:64
	global_load_dwordx4 v[114:117], v[146:147], off offset:128
	global_load_dwordx4 v[118:121], v[146:147], off offset:192
	global_load_dwordx4 v[126:129], v[146:147], off offset:256
	global_load_dwordx4 v[130:133], v[146:147], off offset:320
	global_load_dwordx4 v[134:137], v[146:147], off offset:384
	global_load_dwordx4 v[138:141], v[146:147], off offset:448
	s_mov_b32 s98, 0
	global_load_dwordx4 v[4:7], v[36:37], off offset:1024
	global_load_dwordx4 v[8:11], v[36:37], off offset:2048
	global_load_dwordx4 v[12:15], v[30:31], off
	global_load_dwordx4 v[16:19], v[30:31], off offset:1024
	global_load_dwordx4 v[20:23], v[30:31], off offset:2048
	global_load_dwordx4 v[24:27], v[30:31], off offset:3072
	s_nop 0
	global_load_dwordx4 v[28:31], v[38:39], off
	global_load_dwordx4 v[32:35], v[36:37], off offset:3072
	v_xor_b32_e32 v36, 1, v150
	v_cmp_lt_i32_e32 vcc, v36, v123
	s_mov_b32 s0, 0x800000
	v_readlane_b32 s1, v254, 62
	v_cndmask_b32_e32 v36, v150, v36, vcc
	v_lshlrev_b32_e32 v59, 2, v36
	s_add_i32 s1, s1, 0
	v_readlane_b32 s11, v254, 3
	s_cmpk_gt_i32 s11, 0x1ff
	s_waitcnt vmcnt(5)
	v_mul_f32_e32 v62, v12, v12
	v_mov_b32_e32 v39, v5
	v_mov_b32_e32 v43, v7
	s_waitcnt vmcnt(1)
	v_mov_b32_e32 v38, v29
	v_mov_b32_e32 v42, v31
	v_mov_b32_e32 v37, v4
	v_mov_b32_e32 v41, v6
	v_pk_mul_f32 v[44:45], v[10:11], v[10:11]
	v_pk_mul_f32 v[46:47], v[8:9], v[8:9]
	v_mov_b32_e32 v36, v28
	v_mov_b32_e32 v40, v30
	v_pk_mul_f32 v[38:39], v[38:39], v[38:39]
	v_pk_mul_f32 v[42:43], v[42:43], v[42:43]
	v_pk_mov_b32 v[56:57], v[46:47], v[44:45] op_sel:[1,0]
	v_mov_b32_e32 v47, v45
	v_pk_fma_f32 v[36:37], v[36:37], v[36:37], v[38:39]
	v_pk_fma_f32 v[38:39], v[40:41], v[40:41], v[42:43]
	v_pk_mul_f32 v[48:49], v[18:19], v[18:19]
	v_pk_mul_f32 v[50:51], v[16:17], v[16:17]
	v_mul_f32_e32 v52, v21, v21
	v_mul_f32_e32 v54, v23, v23
	s_waitcnt vmcnt(0)
	v_mul_f32_e32 v44, v33, v33
	v_mul_f32_e32 v58, v35, v35
	v_pk_add_f32 v[46:47], v[56:57], v[46:47]
	v_pk_add_f32 v[36:37], v[36:37], v[38:39]
	v_mul_f32_e32 v63, v13, v13
	v_mul_f32_e32 v64, v14, v14
	v_mul_f32_e32 v65, v15, v15
	v_pk_mov_b32 v[60:61], v[50:51], v[48:49] op_sel:[1,0]
	v_mov_b32_e32 v51, v49
	v_pk_fma_f32 v[48:49], v[20:21], v[20:21], v[52:53] op_sel_hi:[1,1,0]
	v_pk_fma_f32 v[52:53], v[22:23], v[22:23], v[54:55] op_sel_hi:[1,1,0]
	v_pk_fma_f32 v[44:45], v[32:33], v[32:33], v[44:45] op_sel_hi:[1,1,0]
	v_pk_fma_f32 v[54:55], v[34:35], v[34:35], v[58:59] op_sel_hi:[1,1,0]
	v_pk_add_f32 v[40:41], v[46:47], v[46:47] op_sel:[0,1] op_sel_hi:[1,0]
	v_pk_add_f32 v[36:37], v[36:37], v[36:37] op_sel:[0,1] op_sel_hi:[1,0]
	v_mov_b32_e32 v45, v64
	v_mov_b32_e32 v55, v65
	v_mov_b32_e32 v41, v63
	v_mov_b32_e32 v37, v62
	v_pk_add_f32 v[38:39], v[44:45], v[54:55]
	v_pk_add_f32 v[36:37], v[36:37], v[40:41]
	v_pk_add_f32 v[50:51], v[60:61], v[50:51]
	v_pk_add_f32 v[36:37], v[36:37], v[38:39]
	v_mul_f32_e32 v66, v24, v24
	v_mul_f32_e32 v67, v25, v25
	v_mul_f32_e32 v68, v26, v26
	v_mul_f32_e32 v69, v27, v27
	v_pk_add_f32 v[42:43], v[50:51], v[50:51] op_sel:[0,1] op_sel_hi:[1,0]
	v_pk_add_f32 v[36:37], v[36:37], v[36:37] op_sel:[0,1] op_sel_hi:[1,0]
	v_mov_b32_e32 v49, v68
	v_mov_b32_e32 v53, v69
	v_mov_b32_e32 v43, v67
	v_mov_b32_e32 v37, v66
	v_pk_add_f32 v[46:47], v[48:49], v[52:53]
	v_pk_add_f32 v[36:37], v[36:37], v[42:43]
	v_xor_b32_e32 v38, 2, v150
	v_pk_add_f32 v[36:37], v[36:37], v[46:47]
	v_cmp_lt_i32_e32 vcc, v38, v123
	v_add_f32_e32 v36, v36, v37
	ds_bpermute_b32 v37, v59, v36
	v_cndmask_b32_e32 v38, v150, v38, vcc
	v_lshlrev_b32_e32 v38, 2, v38
	s_waitcnt lgkmcnt(0)
	v_add_f32_e32 v36, v36, v37
	ds_bpermute_b32 v37, v38, v36
	v_xor_b32_e32 v38, 4, v150
	v_cmp_lt_i32_e32 vcc, v38, v123
	s_waitcnt lgkmcnt(0)
	v_add_f32_e32 v36, v36, v37
	v_cndmask_b32_e32 v38, v150, v38, vcc
	v_lshlrev_b32_e32 v38, 2, v38
	ds_bpermute_b32 v37, v38, v36
	v_xor_b32_e32 v38, 8, v150
	v_cmp_lt_i32_e32 vcc, v38, v123
	s_waitcnt lgkmcnt(0)
	v_add_f32_e32 v36, v36, v37
	v_cndmask_b32_e32 v38, v150, v38, vcc
	v_lshlrev_b32_e32 v38, 2, v38
	ds_bpermute_b32 v37, v38, v36
	v_cmp_lt_i32_e32 vcc, v122, v123
	s_waitcnt lgkmcnt(0)
	v_add_f32_e32 v36, v36, v37
	v_cndmask_b32_e32 v38, v150, v122, vcc
	v_lshlrev_b32_e32 v38, 2, v38
	ds_bpermute_b32 v37, v38, v36
	v_cmp_lt_i32_e32 vcc, v124, v123
	s_waitcnt lgkmcnt(0)
	v_add_f32_e32 v36, v36, v37
	v_cndmask_b32_e32 v38, v150, v124, vcc
	v_lshlrev_b32_e32 v38, 2, v38
	ds_bpermute_b32 v37, v38, v36
	v_mov_b32_e32 v38, 0x358637bd
	s_waitcnt lgkmcnt(0)
	v_add_f32_e32 v36, v36, v37
	v_fmac_f32_e32 v38, 0x3a000000, v36
	v_mul_f32_e32 v36, 0x4b800000, v38
	v_cmp_gt_f32_e32 vcc, s0, v38
	v_lshl_add_u32 v37, v212, 3, s1
	s_movk_i32 s0, 0x1040
	v_cndmask_b32_e32 v36, v38, v36, vcc
	v_rsq_f32_e32 v36, v36
	s_nop 0
	v_mul_f32_e32 v38, 0x45800000, v36
	v_cndmask_b32_e32 v36, v36, v38, vcc
	v_pk_mul_f32 v[28:29], v[28:29], v[36:37] op_sel_hi:[1,0]
	v_pk_mul_f32 v[30:31], v[30:31], v[36:37] op_sel_hi:[1,0]
	v_pk_mul_f32 v[4:5], v[4:5], v[36:37] op_sel_hi:[1,0]
	v_pk_mul_f32 v[6:7], v[6:7], v[36:37] op_sel_hi:[1,0]
	v_pk_mul_f32 v[8:9], v[8:9], v[36:37] op_sel_hi:[1,0]
	v_cvt_pk_bf16_f32 v28, v28, v29
	v_cvt_pk_bf16_f32 v29, v30, v31
	v_cvt_pk_bf16_f32 v4, v4, v5
	v_cvt_pk_bf16_f32 v5, v6, v7
	v_pk_mul_f32 v[10:11], v[10:11], v[36:37] op_sel_hi:[1,0]
	v_cvt_pk_bf16_f32 v6, v8, v9
	ds_write2st64_b64 v37, v[28:29], v[4:5] offset1:1
	v_pk_mul_f32 v[4:5], v[32:33], v[36:37] op_sel_hi:[1,0]
	v_pk_mul_f32 v[8:9], v[34:35], v[36:37] op_sel_hi:[1,0]
	v_cvt_pk_bf16_f32 v7, v10, v11
	v_cvt_pk_bf16_f32 v4, v4, v5
	v_cvt_pk_bf16_f32 v5, v8, v9
	ds_write2st64_b64 v37, v[6:7], v[4:5] offset0:2 offset1:3
	v_pk_mul_f32 v[4:5], v[12:13], v[36:37] op_sel_hi:[1,0]
	v_pk_mul_f32 v[6:7], v[14:15], v[36:37] op_sel_hi:[1,0]
	v_cvt_pk_bf16_f32 v4, v4, v5
	v_cvt_pk_bf16_f32 v5, v6, v7
	v_pk_mul_f32 v[6:7], v[16:17], v[36:37] op_sel_hi:[1,0]
	v_pk_mul_f32 v[8:9], v[18:19], v[36:37] op_sel_hi:[1,0]
	v_cvt_pk_bf16_f32 v6, v6, v7
	v_cvt_pk_bf16_f32 v7, v8, v9
	ds_write2st64_b64 v37, v[4:5], v[6:7] offset0:4 offset1:5
	v_pk_mul_f32 v[4:5], v[20:21], v[36:37] op_sel_hi:[1,0]
	v_pk_mul_f32 v[6:7], v[22:23], v[36:37] op_sel_hi:[1,0]
	v_cvt_pk_bf16_f32 v4, v4, v5
	v_cvt_pk_bf16_f32 v5, v6, v7
	v_pk_mul_f32 v[6:7], v[24:25], v[36:37] op_sel_hi:[1,0]
	v_pk_mul_f32 v[8:9], v[26:27], v[36:37] op_sel_hi:[1,0]
	v_cvt_pk_bf16_f32 v6, v6, v7
	v_cvt_pk_bf16_f32 v7, v8, v9
	ds_write2st64_b64 v37, v[4:5], v[6:7] offset0:6 offset1:7
	s_waitcnt lgkmcnt(0)
	s_barrier
	s_cbranch_scc1 .LBB0_1548
	s_add_u32 s6, s82, 0x25860000
	s_addc_u32 s7, s83, 0
	s_lshl_b32 s8, s84, 9
	s_add_u32 s2, s82, s8
	s_addc_u32 s3, s83, 0
	v_and_b32_e32 v4, 48, v212
	v_mov_b32_e32 v5, v3
	v_and_b32_e32 v8, 0x70, v0
	v_lshl_add_u64 v[6:7], s[2:3], 0, v[4:5]
	s_mov_b64 s[2:3], 0x2200000
	v_and_b32_e32 v3, 7, v0
	v_or_b32_e32 v4, s8, v4
	v_lshlrev_b32_e32 v5, 2, v1
	v_lshlrev_b32_e32 v8, 2, v8
	s_add_i32 s8, s8, 0
	v_lshl_add_u64 v[6:7], v[6:7], 0, s[2:3]
	v_mad_u32_u24 v3, v3, s0, 0
	v_and_b32_e32 v2, 0x300, v2
	s_movk_i32 s2, 0x80
	v_add3_u32 v10, 0, v8, v5
	v_lshlrev_b32_e32 v8, 9, v0
	v_add_u32_e32 v5, s8, v5
	v_readlane_b32 s8, v254, 2
	v_cmp_lt_u32_e32 vcc, 7, v1
	v_cmp_gt_u32_e64 s[0:1], 32, v212
	v_cmp_gt_u32_e64 s[2:3], s2, v0
	v_and_b32_e32 v11, 0xe000, v8
	v_lshl_or_b32 v8, s11, 4, v1
	s_lshl_b32 s10, s8, 4
	v_add_u32_e32 v1, v3, v4
	v_add_u32_e32 v12, v5, v2
	s_branch .LBB0_1543

.LBB0_1543:
	s_cmp_eq_u32 s98, 0
	s_cbranch_scc1 .Lp6t_w0
	s_cmp_eq_u32 s98, 1
	s_cbranch_scc1 .Lp6t_w1
	v_ashrrev_i32_e32 v9, 31, v8
	v_lshlrev_b64 v[2:3], 12, v[8:9]
	v_lshl_add_u64 v[42:43], v[6:7], 0, v[2:3]
	global_load_dwordx4 v[2:5], v[42:43], off
	global_load_dwordx4 v[14:17], v[42:43], off offset:64
	global_load_dwordx4 v[18:21], v[42:43], off offset:128
	global_load_dwordx4 v[22:25], v[42:43], off offset:192
	global_load_dwordx4 v[26:29], v[42:43], off offset:256
	global_load_dwordx4 v[30:33], v[42:43], off offset:320
	global_load_dwordx4 v[34:37], v[42:43], off offset:384
	global_load_dwordx4 v[38:41], v[42:43], off offset:448
	s_branch .Lp6t_go
.Lp6t_w0:
	s_waitcnt vmcnt(0)
	v_mov_b64_e32 v[2:3], v[74:75]
	v_mov_b64_e32 v[4:5], v[76:77]
	v_mov_b64_e32 v[14:15], v[78:79]
	v_mov_b64_e32 v[16:17], v[80:81]
	v_mov_b64_e32 v[18:19], v[82:83]
	v_mov_b64_e32 v[20:21], v[84:85]
	v_mov_b64_e32 v[22:23], v[86:87]
	v_mov_b64_e32 v[24:25], v[88:89]
	v_mov_b64_e32 v[26:27], v[90:91]
	v_mov_b64_e32 v[28:29], v[92:93]
	v_mov_b64_e32 v[30:31], v[94:95]
	v_mov_b64_e32 v[32:33], v[96:97]
	v_mov_b64_e32 v[34:35], v[98:99]
	v_mov_b64_e32 v[36:37], v[100:101]
	v_mov_b64_e32 v[38:39], v[102:103]
	v_mov_b64_e32 v[40:41], v[104:105]
	s_branch .Lp6t_go
.Lp6t_w1:
	s_waitcnt vmcnt(0)
	v_mov_b64_e32 v[2:3], v[106:107]
	v_mov_b64_e32 v[4:5], v[108:109]
	v_mov_b64_e32 v[14:15], v[110:111]
	v_mov_b64_e32 v[16:17], v[112:113]
	v_mov_b64_e32 v[18:19], v[114:115]
	v_mov_b64_e32 v[20:21], v[116:117]
	v_mov_b64_e32 v[22:23], v[118:119]
	v_mov_b64_e32 v[24:25], v[120:121]
	v_mov_b64_e32 v[26:27], v[126:127]
	v_mov_b64_e32 v[28:29], v[128:129]
	v_mov_b64_e32 v[30:31], v[130:131]
	v_mov_b64_e32 v[32:33], v[132:133]
	v_mov_b64_e32 v[34:35], v[134:135]
	v_mov_b64_e32 v[36:37], v[136:137]
	v_mov_b64_e32 v[38:39], v[138:139]
	v_mov_b64_e32 v[40:41], v[140:141]
.Lp6t_go:
	s_add_i32 s98, s98, 1
	ds_read_b128 v[42:45], v1
	ds_read_b128 v[46:49], v1 offset:64
	ds_read_b128 v[50:53], v1 offset:128
	ds_read_b128 v[54:57], v1 offset:192
	ds_read_b128 v[58:61], v1 offset:256
	ds_read_b128 v[62:65], v1 offset:320
	ds_read_b128 v[66:69], v1 offset:384
	ds_read_b128 v[70:73], v1 offset:448
	s_waitcnt lgkmcnt(7)
	v_cndmask_b32_e64 v45, v45, 0, vcc
	v_cndmask_b32_e64 v44, v44, 0, vcc
	v_cndmask_b32_e64 v43, v43, 0, vcc
	v_cndmask_b32_e64 v42, v42, 0, vcc
	s_waitcnt lgkmcnt(6)
	v_cndmask_b32_e64 v49, v49, 0, vcc
	v_cndmask_b32_e64 v48, v48, 0, vcc
	v_cndmask_b32_e64 v47, v47, 0, vcc
	v_cndmask_b32_e64 v46, v46, 0, vcc
	s_waitcnt lgkmcnt(5)
	v_cndmask_b32_e64 v53, v53, 0, vcc
	v_cndmask_b32_e64 v52, v52, 0, vcc
	v_cndmask_b32_e64 v51, v51, 0, vcc
	v_cndmask_b32_e64 v50, v50, 0, vcc
	s_waitcnt lgkmcnt(4)
	v_cndmask_b32_e64 v57, v57, 0, vcc
	v_cndmask_b32_e64 v56, v56, 0, vcc
	v_cndmask_b32_e64 v55, v55, 0, vcc
	v_cndmask_b32_e64 v54, v54, 0, vcc
	s_waitcnt vmcnt(7)
	v_mfma_f32_16x16x32_bf16 v[2:5], v[42:45], v[2:5], 0
	s_waitcnt vmcnt(6)
	v_mfma_f32_16x16x32_bf16 v[2:5], v[46:49], v[14:17], v[2:5]
	s_waitcnt lgkmcnt(3)
	v_cndmask_b32_e64 v17, v61, 0, vcc
	v_cndmask_b32_e64 v16, v60, 0, vcc
	v_cndmask_b32_e64 v15, v59, 0, vcc
	s_waitcnt vmcnt(5)
	v_mfma_f32_16x16x32_bf16 v[2:5], v[50:53], v[18:21], v[2:5]
	v_cndmask_b32_e64 v14, v58, 0, vcc
	s_waitcnt lgkmcnt(2)
	v_cndmask_b32_e64 v21, v65, 0, vcc
	v_cndmask_b32_e64 v20, v64, 0, vcc
	s_waitcnt vmcnt(4)
	v_mfma_f32_16x16x32_bf16 v[2:5], v[54:57], v[22:25], v[2:5]
	v_cndmask_b32_e64 v19, v63, 0, vcc
	v_cndmask_b32_e64 v18, v62, 0, vcc
	s_waitcnt lgkmcnt(1)
	v_cndmask_b32_e64 v25, v69, 0, vcc
	s_waitcnt vmcnt(3)
	v_mfma_f32_16x16x32_bf16 v[2:5], v[14:17], v[26:29], v[2:5]
	v_cndmask_b32_e64 v24, v68, 0, vcc
	v_cndmask_b32_e64 v23, v67, 0, vcc
	v_cndmask_b32_e64 v22, v66, 0, vcc
	s_waitcnt vmcnt(2)
	v_mfma_f32_16x16x32_bf16 v[2:5], v[18:21], v[30:33], v[2:5]
	s_waitcnt lgkmcnt(0)
	v_cndmask_b32_e64 v17, v73, 0, vcc
	v_cndmask_b32_e64 v16, v72, 0, vcc
	v_cndmask_b32_e64 v15, v71, 0, vcc
	v_cndmask_b32_e64 v14, v70, 0, vcc
	s_waitcnt vmcnt(1)
	v_mfma_f32_16x16x32_bf16 v[2:5], v[22:25], v[34:37], v[2:5]
	s_waitcnt vmcnt(0)
	v_mfma_f32_16x16x32_bf16 v[2:5], v[14:17], v[38:41], v[2:5]
	s_and_saveexec_b64 s[8:9], s[0:1]
	s_cbranch_execz .LBB0_1545
	v_add_u32_e32 v9, 0x8000, v12
	s_nop 4
	ds_write2_b32 v9, v2, v3 offset0:128 offset1:144
	ds_write2_b32 v9, v4, v5 offset0:160 offset1:176

.LBB0_1550:
	v_add_co_u32_e32 v40, vcc, 0x30000, v2
	s_nop 1
	v_addc_co_u32_e32 v41, vcc, 0, v3, vcc
	v_mov_b64_e32 v[36:37], v[2:3]
	global_load_dwordx4 v[4:7], v[36:37], off
	v_lshl_add_u64 v[36:37], v[36:37], 0, s[2:3]
	global_load_dwordx4 v[8:11], v[36:37], off
	v_lshl_add_u64 v[36:37], v[36:37], 0, s[2:3]
	global_load_dwordx4 v[12:15], v[36:37], off
	v_lshl_add_u64 v[36:37], v[36:37], 0, s[2:3]
	global_load_dwordx4 v[16:19], v[36:37], off
	v_lshl_add_u64 v[36:37], v[36:37], 0, s[2:3]
	global_load_dwordx4 v[20:23], v[36:37], off
	v_lshl_add_u64 v[36:37], v[36:37], 0, s[2:3]
	global_load_dwordx4 v[24:27], v[36:37], off
	v_lshl_add_u64 v[36:37], v[36:37], 0, s[2:3]
	global_load_dwordx4 v[28:31], v[36:37], off
	v_lshl_add_u64 v[36:37], v[36:37], 0, s[2:3]
	global_load_dwordx4 v[32:35], v[36:37], off
	s_waitcnt vmcnt(0)
	global_store_dwordx4 v[40:41], v[4:7], off
	s_nop 0
	v_lshl_add_u64 v[40:41], v[40:41], 0, s[2:3]
	global_store_dwordx4 v[40:41], v[8:11], off
	s_nop 0
	v_lshl_add_u64 v[40:41], v[40:41], 0, s[2:3]
	global_store_dwordx4 v[40:41], v[12:15], off
	s_nop 0
	v_lshl_add_u64 v[40:41], v[40:41], 0, s[2:3]
	global_store_dwordx4 v[40:41], v[16:19], off
	s_nop 0
	v_lshl_add_u64 v[40:41], v[40:41], 0, s[2:3]
	global_store_dwordx4 v[40:41], v[20:23], off
	s_nop 0
	v_lshl_add_u64 v[40:41], v[40:41], 0, s[2:3]
	global_store_dwordx4 v[40:41], v[24:27], off
	s_nop 0
	v_lshl_add_u64 v[40:41], v[40:41], 0, s[2:3]
	global_store_dwordx4 v[40:41], v[28:31], off
	s_nop 0
	v_lshl_add_u64 v[40:41], v[40:41], 0, s[2:3]
	global_store_dwordx4 v[40:41], v[32:35], off

.LBB0_1974:
	v_readlane_b32 s0, v254, 2
	s_add_i32 s0, s0, -1
	v_readlane_b32 s1, v254, 3
	s_cmp_lg_u32 s1, s0
	s_cbranch_scc1 .LBB0_1976
	s_mov_b32 s85, 0
	s_lshl_b64 s[0:1], s[84:85], 13
	s_add_u32 s2, s82, s0
	v_lshlrev_b32_e32 v88, 4, v212
	v_mov_b32_e32 v89, 0
	s_addc_u32 s3, s83, s1
	s_waitcnt vmcnt(4)
	v_lshl_add_u64 v[12:13], s[2:3], 0, v[88:89]
	s_mov_b64 s[2:3], 0x25890000
	v_lshl_add_u64 v[14:15], v[12:13], 0, s[2:3]
	s_mov_b32 s2, 0x25891000
	v_add_co_u32_e32 v20, vcc, s2, v12
	global_load_dwordx4 v[48:51], v[14:15], off offset:1024
	global_load_dwordx4 v[36:39], v[14:15], off offset:2048
	v_addc_co_u32_e32 v21, vcc, 0, v13, vcc
	global_load_dwordx4 v[16:19], v[20:21], off
	global_load_dwordx4 v[8:11], v[20:21], off offset:1024
	s_waitcnt lgkmcnt(0)
	global_load_dwordx4 v[4:7], v[20:21], off offset:2048
	global_load_dwordx4 v[0:3], v[20:21], off offset:3072
	v_add_co_u32_e32 v20, vcc, 0x25890000, v12
	s_mov_b32 s2, 0x258a1000
	s_nop 0
	v_addc_co_u32_e32 v21, vcc, 0, v13, vcc
	global_load_dwordx4 v[68:71], v[20:21], off
	global_load_dwordx4 v[28:31], v[14:15], off offset:3072
	v_mbcnt_lo_u32_b32 v14, -1, 0
	v_mbcnt_hi_u32_b32 v59, -1, v14
	v_and_b32_e32 v14, 64, v59
	v_xor_b32_e32 v15, 1, v59
	v_add_u32_e32 v62, 64, v14
	v_cmp_lt_i32_e32 vcc, v15, v62
	v_mov_b32_e32 v121, 0x358637bd
	s_mov_b64 s[4:5], 0x25880000
	v_cndmask_b32_e32 v14, v59, v15, vcc
	v_lshlrev_b32_e32 v91, 2, v14
	v_add_co_u32_e32 v14, vcc, s2, v12
	s_mov_b64 s[2:3], 0x258a0000
	s_nop 0
	v_addc_co_u32_e32 v15, vcc, 0, v13, vcc
	global_load_dwordx4 v[20:23], v[14:15], off offset:-4096
	global_load_dwordx4 v[92:95], v[14:15], off offset:1024
	global_load_dwordx4 v[122:125], v[14:15], off offset:2048
	s_add_u32 s0, s80, s0
	s_addc_u32 s1, s81, s1
	global_load_dwordx4 v[126:129], v[14:15], off offset:3072
	s_waitcnt vmcnt(11)
	v_mov_b32_e32 v27, v49
	v_mov_b32_e32 v35, v51
	v_mov_b32_e32 v25, v48
	v_mov_b32_e32 v33, v50
	s_waitcnt vmcnt(10)
	v_pk_mul_f32 v[40:41], v[38:39], v[38:39]
	v_pk_mul_f32 v[42:43], v[36:37], v[36:37]
	s_waitcnt vmcnt(8)
	v_pk_mul_f32 v[44:45], v[10:11], v[10:11]
	v_pk_mov_b32 v[56:57], v[42:43], v[40:41] op_sel:[1,0]
	v_mov_b32_e32 v43, v41
	s_waitcnt vmcnt(5)
	v_mov_b32_e32 v26, v69
	v_mov_b32_e32 v34, v71
	v_mov_b32_e32 v24, v68
	v_mov_b32_e32 v32, v70
	v_pk_mul_f32 v[26:27], v[26:27], v[26:27]
	v_pk_mul_f32 v[34:35], v[34:35], v[34:35]
	v_pk_fma_f32 v[24:25], v[24:25], v[24:25], v[26:27]
	v_pk_fma_f32 v[26:27], v[32:33], v[32:33], v[34:35]
	v_pk_mul_f32 v[46:47], v[8:9], v[8:9]
	v_mul_f32_e32 v52, v5, v5
	v_mul_f32_e32 v54, v7, v7
	s_waitcnt vmcnt(4)
	v_mul_f32_e32 v40, v29, v29
	v_mul_f32_e32 v58, v31, v31
	v_pk_add_f32 v[42:43], v[56:57], v[42:43]
	v_pk_add_f32 v[24:25], v[24:25], v[26:27]
	v_mul_f32_e32 v63, v16, v16
	v_mul_f32_e32 v64, v17, v17
	v_mul_f32_e32 v65, v18, v18
	v_mul_f32_e32 v66, v19, v19
	v_pk_mov_b32 v[60:61], v[46:47], v[44:45] op_sel:[1,0]
	v_mov_b32_e32 v47, v45
	v_pk_fma_f32 v[44:45], v[4:5], v[4:5], v[52:53] op_sel_hi:[1,1,0]
	v_pk_fma_f32 v[52:53], v[6:7], v[6:7], v[54:55] op_sel_hi:[1,1,0]
	v_pk_fma_f32 v[40:41], v[28:29], v[28:29], v[40:41] op_sel_hi:[1,1,0]
	v_pk_fma_f32 v[54:55], v[30:31], v[30:31], v[58:59] op_sel_hi:[1,1,0]
	v_pk_add_f32 v[32:33], v[42:43], v[42:43] op_sel:[0,1] op_sel_hi:[1,0]
	v_pk_add_f32 v[24:25], v[24:25], v[24:25] op_sel:[0,1] op_sel_hi:[1,0]
	v_mov_b32_e32 v41, v65
	v_mov_b32_e32 v55, v66
	v_mov_b32_e32 v33, v64
	v_mov_b32_e32 v25, v63
	v_pk_add_f32 v[26:27], v[40:41], v[54:55]
	v_pk_add_f32 v[24:25], v[24:25], v[32:33]
	v_pk_add_f32 v[46:47], v[60:61], v[46:47]
	v_pk_add_f32 v[24:25], v[24:25], v[26:27]
	v_mul_f32_e32 v67, v0, v0
	v_mul_f32_e32 v72, v1, v1
	v_mul_f32_e32 v73, v2, v2
	v_mul_f32_e32 v74, v3, v3
	v_pk_add_f32 v[34:35], v[46:47], v[46:47] op_sel:[0,1] op_sel_hi:[1,0]
	v_pk_add_f32 v[24:25], v[24:25], v[24:25] op_sel:[0,1] op_sel_hi:[1,0]
	v_mov_b32_e32 v45, v73
	v_mov_b32_e32 v53, v74
	v_mov_b32_e32 v35, v72
	v_mov_b32_e32 v25, v67
	v_pk_add_f32 v[42:43], v[44:45], v[52:53]
	v_pk_add_f32 v[24:25], v[24:25], v[34:35]
	v_xor_b32_e32 v26, 2, v59
	v_pk_add_f32 v[24:25], v[24:25], v[42:43]
	v_cmp_lt_i32_e32 vcc, v26, v62
	v_add_f32_e32 v24, v24, v25
	ds_bpermute_b32 v25, v91, v24
	v_lshl_add_u64 v[40:41], v[12:13], 0, s[2:3]
	s_mov_b32 s2, 0x800000
	s_mov_b32 s3, 0x25881000
	v_lshl_add_u64 v[54:55], s[74:75], 0, v[88:89]
	s_waitcnt lgkmcnt(0)
	v_add_f32_e32 v32, v24, v25
	v_cndmask_b32_e32 v24, v59, v26, vcc
	v_lshlrev_b32_e32 v116, 2, v24
	ds_bpermute_b32 v33, v116, v32
	global_load_dwordx4 v[24:27], v[40:41], off offset:1024
	s_waitcnt lgkmcnt(0)
	v_add_f32_e32 v42, v32, v33
	v_xor_b32_e32 v32, 4, v59
	v_cmp_lt_i32_e32 vcc, v32, v62
	s_nop 1
	v_cndmask_b32_e32 v32, v59, v32, vcc
	v_lshlrev_b32_e32 v117, 2, v32
	ds_bpermute_b32 v43, v117, v42
	global_load_dwordx4 v[32:35], v[40:41], off offset:2048
	s_waitcnt lgkmcnt(0)
	v_add_f32_e32 v44, v42, v43
	v_xor_b32_e32 v42, 8, v59
	v_cmp_lt_i32_e32 vcc, v42, v62
	s_nop 1
	v_cndmask_b32_e32 v45, v59, v42, vcc
	v_lshlrev_b32_e32 v118, 2, v45
	ds_bpermute_b32 v45, v118, v44
	global_load_dwordx4 v[40:43], v[40:41], off offset:3072
	s_waitcnt lgkmcnt(0)
	v_add_f32_e32 v52, v44, v45
	v_xor_b32_e32 v44, 16, v59
	v_cmp_lt_i32_e32 vcc, v44, v62
	s_nop 1
	v_cndmask_b32_e32 v44, v59, v44, vcc
	v_lshlrev_b32_e32 v119, 2, v44
	ds_bpermute_b32 v53, v119, v52
	global_load_dwordx4 v[44:47], v[14:15], off
	s_waitcnt vmcnt(7)
	v_mul_f32_e32 v20, 0xbfb8aa3b, v20
	v_exp_f32_e32 v142, v20
	v_mul_f32_e32 v20, 0xbfb8aa3b, v21
	s_waitcnt lgkmcnt(0)
	v_add_f32_e32 v52, v52, v53
	v_xor_b32_e32 v53, 32, v59
	v_cmp_lt_i32_e32 vcc, v53, v62
	v_exp_f32_e32 v143, v20
	v_mul_f32_e32 v20, 0xbfb8aa3b, v22
	v_cndmask_b32_e32 v53, v59, v53, vcc
	v_lshlrev_b32_e32 v120, 2, v53
	ds_bpermute_b32 v53, v120, v52
	v_exp_f32_e32 v144, v20
	v_mul_f32_e32 v20, 0xbfb8aa3b, v23
	v_exp_f32_e32 v145, v20
	s_waitcnt lgkmcnt(0)
	v_add_f32_e32 v52, v52, v53
	v_fmamk_f32 v52, v52, 0x3a000000, v121
	v_mul_f32_e32 v53, 0x4b800000, v52
	v_cmp_gt_f32_e32 vcc, s2, v52
	s_waitcnt vmcnt(3)
	v_mul_f32_e32 v20, 0xbfb8aa3b, v24
	v_cndmask_b32_e32 v52, v52, v53, vcc
	v_rsq_f32_e32 v56, v52
	v_lshl_add_u64 v[52:53], v[12:13], 0, s[4:5]
	v_exp_f32_e32 v146, v20
	v_mul_f32_e32 v20, 0xbfb8aa3b, v25
	v_mul_f32_e32 v57, 0x45800000, v56
	v_cndmask_b32_e32 v90, v56, v57, vcc
	v_add_co_u32_e32 v96, vcc, s3, v12
	v_exp_f32_e32 v147, v20
	s_nop 0
	v_addc_co_u32_e32 v97, vcc, 0, v13, vcc
	global_load_dwordx4 v[130:133], v88, s[74:75]
	global_load_dwordx4 v[12:15], v[96:97], off offset:3072
	global_load_dwordx4 v[60:63], v[52:53], off offset:3072
	global_load_dwordx4 v[84:87], v[52:53], off offset:1024
	global_load_dwordx4 v[76:79], v[52:53], off offset:2048
	global_load_dwordx4 v[134:137], v88, s[74:75] offset:1024
	global_load_dwordx4 v[80:83], v88, s[74:75] offset:2048
	global_load_dwordx4 v[72:75], v88, s[74:75] offset:3072
	global_load_dwordx4 v[138:141], v[96:97], off offset:-4096
	global_load_dwordx4 v[56:59], v[96:97], off
	v_mul_f32_e32 v20, 0xbfb8aa3b, v26
	v_exp_f32_e32 v148, v20
	v_mul_f32_e32 v20, 0xbfb8aa3b, v27
	v_exp_f32_e32 v149, v20
	s_waitcnt vmcnt(12)
	v_mul_f32_e32 v20, 0xbfb8aa3b, v32
	v_exp_f32_e32 v114, v20
	v_mul_f32_e32 v20, 0xbfb8aa3b, v33
	v_exp_f32_e32 v115, v20
	v_mul_f32_e32 v20, 0xbfb8aa3b, v34
	v_exp_f32_e32 v112, v20
	v_mul_f32_e32 v20, 0xbfb8aa3b, v35
	v_exp_f32_e32 v113, v20
	s_waitcnt vmcnt(11)
	v_mul_f32_e32 v20, 0xbfb8aa3b, v40
	v_exp_f32_e32 v110, v20
	v_mul_f32_e32 v20, 0xbfb8aa3b, v41
	v_exp_f32_e32 v111, v20
	v_mul_f32_e32 v20, 0xbfb8aa3b, v42
	v_exp_f32_e32 v108, v20
	s_waitcnt vmcnt(10)
	v_mul_f32_e32 v22, 0xbfb8aa3b, v44
	v_exp_f32_e32 v106, v22
	v_mul_f32_e32 v22, 0xbfb8aa3b, v45
	v_exp_f32_e32 v107, v22
	v_mul_f32_e32 v22, 0xbfb8aa3b, v46
	v_exp_f32_e32 v104, v22
	v_mul_f32_e32 v22, 0xbfb8aa3b, v47
	v_exp_f32_e32 v105, v22
	v_mul_f32_e32 v22, 0xbfb8aa3b, v92
	v_exp_f32_e32 v102, v22
	v_mul_f32_e32 v22, 0xbfb8aa3b, v93
	v_exp_f32_e32 v103, v22
	v_mul_f32_e32 v22, 0xbfb8aa3b, v94
	v_exp_f32_e32 v100, v22
	v_mul_f32_e32 v22, 0xbfb8aa3b, v95
	v_mul_f32_e32 v20, 0xbfb8aa3b, v43
	s_movk_i32 s3, 0x1000
	v_exp_f32_e32 v101, v22
	v_mul_f32_e32 v22, 0xbfb8aa3b, v122
	v_pk_mul_f32 v[68:69], v[90:91], v[68:69] op_sel_hi:[0,1]
	v_exp_f32_e32 v109, v20
	v_add_co_u32_e32 v20, vcc, s3, v54
	v_exp_f32_e32 v98, v22
	v_mul_f32_e32 v22, 0xbfb8aa3b, v123
	v_pk_add_f32 v[122:123], v[142:143], 1.0 op_sel_hi:[1,0]
	v_addc_co_u32_e32 v21, vcc, 0, v55, vcc
	v_exp_f32_e32 v99, v22
	v_mul_f32_e32 v22, 0xbfb8aa3b, v124
	global_load_dwordx4 v[64:67], v[20:21], off
	global_load_dwordx4 v[52:55], v[20:21], off offset:1024
	global_load_dwordx4 v[44:47], v[96:97], off offset:1024
	global_load_dwordx4 v[32:35], v[96:97], off offset:2048
	v_exp_f32_e32 v96, v22
	v_mul_f32_e32 v22, 0xbfb8aa3b, v125
	global_load_dwordx4 v[40:43], v[20:21], off offset:2048
	global_load_dwordx4 v[24:27], v[20:21], off offset:3072
	v_mul_f32_e32 v20, 0xbfb8aa3b, v126
	v_exp_f32_e32 v94, v20
	v_mul_f32_e32 v20, 0xbfb8aa3b, v127
	v_mul_f32_e32 v92, 0xbfb8aa3b, v128
	v_pk_mul_f32 v[70:71], v[90:91], v[70:71] op_sel_hi:[0,1]
	v_mul_f32_e32 v93, 0xbfb8aa3b, v129
	v_pk_mul_f32 v[48:49], v[90:91], v[48:49] op_sel_hi:[0,1]
	v_pk_mul_f32 v[50:51], v[90:91], v[50:51] op_sel_hi:[0,1]
	v_pk_mul_f32 v[36:37], v[90:91], v[36:37] op_sel_hi:[0,1]
	v_pk_add_f32 v[114:115], v[114:115], 1.0 op_sel_hi:[1,0]
	v_pk_mul_f32 v[38:39], v[90:91], v[38:39] op_sel_hi:[0,1]
	v_pk_mul_f32 v[28:29], v[90:91], v[28:29] op_sel_hi:[0,1]
	v_pk_mul_f32 v[30:31], v[90:91], v[30:31] op_sel_hi:[0,1]
	v_pk_mul_f32 v[16:17], v[90:91], v[16:17] op_sel_hi:[0,1]
	v_pk_mul_f32 v[18:19], v[90:91], v[18:19] op_sel_hi:[0,1]
	v_pk_mul_f32 v[8:9], v[90:91], v[8:9] op_sel_hi:[0,1]
	v_pk_mul_f32 v[10:11], v[90:91], v[10:11] op_sel_hi:[0,1]
	v_pk_mul_f32 v[4:5], v[90:91], v[4:5] op_sel_hi:[0,1]
	v_exp_f32_e32 v97, v22
	v_pk_mul_f32 v[6:7], v[90:91], v[6:7] op_sel_hi:[0,1]
	v_exp_f32_e32 v95, v20
	s_waitcnt vmcnt(15)
	v_pk_mul_f32 v[68:69], v[130:131], v[68:69]
	v_pk_mul_f32 v[70:71], v[132:133], v[70:71]
	v_div_scale_f32 v124, s[4:5], v123, v123, v69
	v_rcp_f32_e32 v125, v124
	s_waitcnt vmcnt(9)
	v_pk_mul_f32 v[36:37], v[80:81], v[36:37]
	v_pk_mul_f32 v[38:39], v[82:83], v[38:39]
	v_pk_add_f32 v[82:83], v[112:113], 1.0 op_sel_hi:[1,0]
	v_fma_f32 v126, -v124, v125, 1.0
	v_fmac_f32_e32 v125, v126, v125
	v_div_scale_f32 v126, vcc, v69, v123, v69
	v_mul_f32_e32 v127, v126, v125
	v_fma_f32 v128, -v124, v127, v126
	v_fmac_f32_e32 v127, v128, v125
	v_fma_f32 v124, -v124, v127, v126
	v_div_scale_f32 v126, s[4:5], v122, v122, v68
	v_rcp_f32_e32 v128, v126
	v_div_fmas_f32 v124, v124, v125, v127
	v_div_fixup_f32 v69, v124, v123, v69
	s_waitcnt vmcnt(8)
	v_pk_mul_f32 v[28:29], v[72:73], v[28:29]
	v_fma_f32 v123, -v126, v128, 1.0
	v_fmac_f32_e32 v128, v123, v128
	v_div_scale_f32 v123, vcc, v68, v122, v68
	v_mul_f32_e32 v127, v123, v128
	v_fma_f32 v124, -v126, v127, v123
	v_fmac_f32_e32 v127, v124, v128
	v_pk_add_f32 v[124:125], v[144:145], 1.0 op_sel_hi:[1,0]
	v_fma_f32 v123, -v126, v127, v123
	v_div_scale_f32 v126, s[4:5], v125, v125, v71
	v_rcp_f32_e32 v129, v126
	v_div_fmas_f32 v123, v123, v128, v127
	v_div_fixup_f32 v68, v123, v122, v68
	s_waitcnt vmcnt(7)
	v_pk_add_f32 v[68:69], v[138:139], v[68:69]
	v_fma_f32 v122, -v126, v129, 1.0
	v_fmac_f32_e32 v129, v122, v129
	v_div_scale_f32 v122, vcc, v71, v125, v71
	v_mul_f32_e32 v123, v122, v129
	v_fma_f32 v127, -v126, v123, v122
	v_fmac_f32_e32 v123, v127, v129
	v_fma_f32 v122, -v126, v123, v122
	v_div_scale_f32 v126, s[4:5], v124, v124, v70
	v_rcp_f32_e32 v128, v126
	v_div_fmas_f32 v122, v122, v129, v123
	v_div_fixup_f32 v71, v122, v125, v71
	v_pk_add_f32 v[72:73], v[110:111], 1.0 op_sel_hi:[1,0]
	v_fma_f32 v122, -v126, v128, 1.0
	v_fmac_f32_e32 v128, v122, v128
	v_div_scale_f32 v122, vcc, v70, v124, v70
	v_mul_f32_e32 v125, v122, v128
	v_fma_f32 v123, -v126, v125, v122
	v_fmac_f32_e32 v125, v123, v128
	v_fma_f32 v129, -v126, v125, v122
	v_pk_mul_f32 v[122:123], v[134:135], v[48:49]
	v_pk_add_f32 v[126:127], v[146:147], 1.0 op_sel_hi:[1,0]
	v_div_fmas_f32 v48, v129, v128, v125
	v_div_scale_f32 v130, s[4:5], v127, v127, v123
	v_rcp_f32_e32 v131, v130
	v_div_fixup_f32 v70, v48, v124, v70
	v_pk_add_f32 v[48:49], v[140:141], v[70:71]
	v_pk_add_f32 v[128:129], v[148:149], 1.0 op_sel_hi:[1,0]
	v_fma_f32 v70, -v130, v131, 1.0
	v_fmac_f32_e32 v131, v70, v131
	v_div_scale_f32 v70, vcc, v123, v127, v123
	v_mul_f32_e32 v71, v70, v131
	v_fma_f32 v124, -v130, v71, v70
	v_fmac_f32_e32 v71, v124, v131
	v_div_scale_f32 v124, s[4:5], v126, v126, v122
	v_fma_f32 v70, -v130, v71, v70
	v_rcp_f32_e32 v130, v124
	v_div_fmas_f32 v70, v70, v131, v71
	v_div_fixup_f32 v71, v70, v127, v123
	v_pk_mul_f32 v[30:31], v[74:75], v[30:31]
	v_fma_f32 v70, -v124, v130, 1.0
	v_fmac_f32_e32 v130, v70, v130
	v_div_scale_f32 v70, vcc, v122, v126, v122
	v_mul_f32_e32 v123, v70, v130
	v_fma_f32 v125, -v124, v123, v70
	v_fmac_f32_e32 v123, v125, v130
	v_fma_f32 v70, -v124, v123, v70
	v_pk_mul_f32 v[124:125], v[136:137], v[50:51]
	v_div_fmas_f32 v50, v70, v130, v123
	v_div_scale_f32 v127, s[4:5], v129, v129, v125
	v_rcp_f32_e32 v131, v127
	v_div_fixup_f32 v70, v50, v126, v122
	v_pk_add_f32 v[50:51], v[84:85], v[70:71]
	s_waitcnt vmcnt(5)
	v_pk_mul_f32 v[64:65], v[64:65], v[16:17]
	v_fma_f32 v70, -v127, v131, 1.0
	v_fmac_f32_e32 v131, v70, v131
	v_div_scale_f32 v70, vcc, v125, v129, v125
	v_mul_f32_e32 v71, v70, v131
	v_fma_f32 v84, -v127, v71, v70
	v_fmac_f32_e32 v71, v84, v131
	v_div_scale_f32 v84, s[4:5], v128, v128, v124
	v_rcp_f32_e32 v85, v84
	v_fma_f32 v70, -v127, v71, v70
	v_div_fmas_f32 v70, v70, v131, v71
	v_div_fixup_f32 v71, v70, v129, v125
	v_fma_f32 v70, -v84, v85, 1.0
	v_fmac_f32_e32 v85, v70, v85
	v_div_scale_f32 v70, vcc, v124, v128, v124
	v_mul_f32_e32 v122, v70, v85
	v_fma_f32 v123, -v84, v122, v70
	v_fmac_f32_e32 v122, v123, v85
	v_fma_f32 v70, -v84, v122, v70
	v_div_fmas_f32 v70, v70, v85, v122
	v_div_fixup_f32 v70, v70, v128, v124
	v_pk_add_f32 v[70:71], v[86:87], v[70:71]
	v_mov_b32_e32 v86, v69
	v_mov_b32_e32 v87, v51
	v_mov_b32_e32 v84, v68
	v_mov_b32_e32 v85, v50
	v_pk_mul_f32 v[86:87], v[86:87], v[86:87]
	v_mov_b32_e32 v122, v49
	v_mov_b32_e32 v123, v71
	v_div_scale_f32 v124, s[4:5], v115, v115, v37
	v_pk_fma_f32 v[84:85], v[84:85], v[84:85], v[86:87]
	v_mov_b32_e32 v86, v48
	v_mov_b32_e32 v87, v70
	v_pk_mul_f32 v[122:123], v[122:123], v[122:123]
	v_rcp_f32_e32 v125, v124
	v_pk_fma_f32 v[80:81], v[86:87], v[86:87], v[122:123]
	v_pk_mul_f32 v[66:67], v[66:67], v[18:19]
	v_pk_add_f32 v[80:81], v[84:85], v[80:81]
	s_waitcnt vmcnt(4)
	v_pk_mul_f32 v[8:9], v[52:53], v[8:9]
	v_pk_add_f32 v[80:81], v[80:81], v[80:81] op_sel:[0,1] op_sel_hi:[1,0]
	v_pk_mul_f32 v[10:11], v[54:55], v[10:11]
	v_fma_f32 v81, -v124, v125, 1.0
	v_fmac_f32_e32 v125, v81, v125
	v_div_scale_f32 v81, vcc, v37, v115, v37
	v_mul_f32_e32 v84, v81, v125
	v_fma_f32 v85, -v124, v84, v81
	v_fmac_f32_e32 v84, v85, v125
	v_div_scale_f32 v85, s[4:5], v114, v114, v36
	v_rcp_f32_e32 v86, v85
	v_fma_f32 v81, -v124, v84, v81
	v_div_fmas_f32 v81, v81, v125, v84
	v_div_fixup_f32 v37, v81, v115, v37
	v_fma_f32 v81, -v85, v86, 1.0
	v_fmac_f32_e32 v86, v81, v86
	v_div_scale_f32 v81, vcc, v36, v114, v36
	v_mul_f32_e32 v84, v81, v86
	v_fma_f32 v87, -v85, v84, v81
	v_fmac_f32_e32 v84, v87, v86
	v_fma_f32 v81, -v85, v84, v81
	v_div_scale_f32 v85, s[4:5], v83, v83, v39
	v_rcp_f32_e32 v87, v85
	v_div_fmas_f32 v81, v81, v86, v84
	v_div_fixup_f32 v36, v81, v114, v36
	v_pk_add_f32 v[36:37], v[76:77], v[36:37]
	v_fma_f32 v76, -v85, v87, 1.0
	v_fmac_f32_e32 v87, v76, v87
	v_div_scale_f32 v76, vcc, v39, v83, v39
	v_mul_f32_e32 v77, v76, v87
	v_fma_f32 v81, -v85, v77, v76
	v_fmac_f32_e32 v77, v81, v87
	v_div_scale_f32 v81, s[4:5], v82, v82, v38
	v_rcp_f32_e32 v84, v81
	v_fma_f32 v76, -v85, v77, v76
	v_div_fmas_f32 v76, v76, v87, v77
	v_div_fixup_f32 v39, v76, v83, v39
	v_fma_f32 v76, -v81, v84, 1.0
	v_fmac_f32_e32 v84, v76, v84
	v_div_scale_f32 v76, vcc, v38, v82, v38
	v_mul_f32_e32 v77, v76, v84
	v_fma_f32 v83, -v81, v77, v76
	v_fmac_f32_e32 v77, v83, v84
	v_fma_f32 v76, -v81, v77, v76
	v_div_fmas_f32 v76, v76, v84, v77
	v_div_fixup_f32 v38, v76, v82, v38
	v_pk_add_f32 v[38:39], v[78:79], v[38:39]
	v_div_scale_f32 v81, s[4:5], v73, v73, v29
	v_mov_b32_e32 v78, v37
	v_mov_b32_e32 v79, v39
	v_rcp_f32_e32 v82, v81
	v_mov_b32_e32 v76, v36
	v_mov_b32_e32 v77, v38
	v_pk_mul_f32 v[78:79], v[78:79], v[78:79]
	v_pk_add_f32 v[54:55], v[100:101], 1.0 op_sel_hi:[1,0]
	v_pk_fma_f32 v[76:77], v[76:77], v[76:77], v[78:79]
	s_waitcnt vmcnt(1)
	v_pk_mul_f32 v[4:5], v[40:41], v[4:5]
	v_pk_add_f32 v[76:77], v[76:77], v[76:77] op_sel:[0,1] op_sel_hi:[1,0]
	v_pk_add_f32 v[40:41], v[98:99], 1.0 op_sel_hi:[1,0]
	v_fma_f32 v77, -v81, v82, 1.0
	v_fmac_f32_e32 v82, v77, v82
	v_div_scale_f32 v77, vcc, v29, v73, v29
	v_mul_f32_e32 v78, v77, v82
	v_fma_f32 v79, -v81, v78, v77
	v_fmac_f32_e32 v78, v79, v82
	v_div_scale_f32 v79, s[4:5], v72, v72, v28
	v_fma_f32 v77, -v81, v78, v77
	v_rcp_f32_e32 v81, v79
	v_div_fmas_f32 v77, v77, v82, v78
	v_div_fixup_f32 v29, v77, v73, v29
	v_pk_mul_f32 v[6:7], v[42:43], v[6:7]
	v_fma_f32 v73, -v79, v81, 1.0
	v_fmac_f32_e32 v81, v73, v81
	v_div_scale_f32 v73, vcc, v28, v72, v28
	v_mul_f32_e32 v77, v73, v81
	v_fma_f32 v78, -v79, v77, v73
	v_fmac_f32_e32 v77, v78, v81
	v_fma_f32 v73, -v79, v77, v73
	v_div_fmas_f32 v73, v73, v81, v77
	v_div_fixup_f32 v28, v73, v72, v28
	v_pk_add_f32 v[72:73], v[108:109], 1.0 op_sel_hi:[1,0]
	v_pk_add_f32 v[28:29], v[60:61], v[28:29]
	v_div_scale_f32 v74, s[4:5], v73, v73, v31
	v_rcp_f32_e32 v75, v74
	v_mul_f32_e32 v60, v29, v29
	v_pk_fma_f32 v[60:61], v[28:29], v[28:29], v[60:61] op_sel_hi:[1,1,0]
	v_pk_mul_f32 v[0:1], v[90:91], v[0:1] op_sel_hi:[0,1]
	v_fma_f32 v61, -v74, v75, 1.0
	v_fmac_f32_e32 v75, v61, v75
	v_div_scale_f32 v61, vcc, v31, v73, v31
	v_mul_f32_e32 v77, v61, v75
	v_fma_f32 v78, -v74, v77, v61
	v_fmac_f32_e32 v77, v78, v75
	v_fma_f32 v61, -v74, v77, v61
	v_div_scale_f32 v74, s[4:5], v72, v72, v30
	v_rcp_f32_e32 v78, v74
	v_div_fmas_f32 v61, v61, v75, v77
	v_div_fixup_f32 v31, v61, v73, v31
	s_waitcnt vmcnt(0)
	v_pk_mul_f32 v[0:1], v[24:25], v[0:1]
	v_fma_f32 v61, -v74, v78, 1.0
	v_fmac_f32_e32 v78, v61, v78
	v_div_scale_f32 v61, vcc, v30, v72, v30
	v_mul_f32_e32 v73, v61, v78
	v_fma_f32 v75, -v74, v73, v61
	v_fmac_f32_e32 v73, v75, v78
	v_fma_f32 v61, -v74, v73, v61
	v_div_fmas_f32 v61, v61, v78, v73
	v_div_fixup_f32 v30, v61, v72, v30
	v_pk_add_f32 v[72:73], v[106:107], 1.0 op_sel_hi:[1,0]
	v_pk_add_f32 v[16:17], v[62:63], v[30:31]
	v_div_scale_f32 v61, s[4:5], v73, v73, v65
	v_rcp_f32_e32 v74, v61
	v_mul_f32_e32 v30, v17, v17
	v_pk_fma_f32 v[62:63], v[16:17], v[16:17], v[30:31] op_sel_hi:[1,1,0]
	v_pk_add_f32 v[24:25], v[94:95], 1.0 op_sel_hi:[1,0]
	v_fma_f32 v30, -v61, v74, 1.0
	v_fmac_f32_e32 v74, v30, v74
	v_div_scale_f32 v30, vcc, v65, v73, v65
	v_mul_f32_e32 v31, v30, v74
	v_fma_f32 v63, -v61, v31, v30
	v_fmac_f32_e32 v31, v63, v74
	v_fma_f32 v30, -v61, v31, v30
	v_div_scale_f32 v61, s[4:5], v72, v72, v64
	v_rcp_f32_e32 v63, v61
	v_div_fmas_f32 v30, v30, v74, v31
	v_div_fixup_f32 v31, v30, v73, v65
	v_pk_add_f32 v[74:75], v[104:105], 1.0 op_sel_hi:[1,0]
	v_fma_f32 v30, -v61, v63, 1.0
	v_fmac_f32_e32 v63, v30, v63
	v_div_scale_f32 v30, vcc, v64, v72, v64
	v_mul_f32_e32 v65, v30, v63
	v_fma_f32 v73, -v61, v65, v30
	v_fmac_f32_e32 v65, v73, v63
	v_fma_f32 v30, -v61, v65, v30
	v_div_scale_f32 v61, s[4:5], v75, v75, v67
	v_div_fmas_f32 v30, v30, v63, v65
	v_rcp_f32_e32 v63, v61
	v_div_fixup_f32 v30, v30, v72, v64
	v_pk_add_f32 v[18:19], v[56:57], v[30:31]
	global_load_dwordx4 v[20:23], v88, s[78:79]
	global_load_dwordx4 v[188:191], v88, s[78:79] offset:1024
	global_load_dwordx4 v[192:195], v88, s[78:79] offset:2048
	global_load_dwordx4 v[196:199], v88, s[78:79] offset:3072
	v_add_u32_e32 v220, 0x1000, v88
	global_load_dwordx4 v[200:203], v220, s[78:79]
	global_load_dwordx4 v[204:207], v220, s[78:79] offset:1024
	global_load_dwordx4 v[208:211], v220, s[78:79] offset:2048
	global_load_dwordx4 v[214:217], v220, s[78:79] offset:3072
	v_fma_f32 v30, -v61, v63, 1.0
	v_fmac_f32_e32 v63, v30, v63
	v_div_scale_f32 v30, vcc, v67, v75, v67
	v_mul_f32_e32 v31, v30, v63
	v_fma_f32 v64, -v61, v31, v30
	v_fmac_f32_e32 v31, v64, v63
	v_fma_f32 v30, -v61, v31, v30
	v_div_scale_f32 v61, s[4:5], v74, v74, v66
	v_rcp_f32_e32 v64, v61
	v_div_fmas_f32 v30, v30, v63, v31
	v_div_fixup_f32 v31, v30, v75, v67
	v_pk_mul_f32 v[56:57], v[18:19], v[18:19]
	v_fma_f32 v30, -v61, v64, 1.0
	v_fmac_f32_e32 v64, v30, v64
	v_div_scale_f32 v30, vcc, v66, v74, v66
	v_mul_f32_e32 v63, v30, v64
	v_fma_f32 v65, -v61, v63, v30
	v_fmac_f32_e32 v63, v65, v64
	v_fma_f32 v30, -v61, v63, v30
	v_div_fmas_f32 v30, v30, v64, v63
	v_div_fixup_f32 v30, v30, v74, v66
	v_pk_add_f32 v[30:31], v[58:59], v[30:31]
	v_mov_b32_e32 v81, v56
	v_pk_mul_f32 v[58:59], v[30:31], v[30:31]
	v_mov_b32_e32 v77, v57
	v_mov_b32_e32 v61, v58
	v_mov_b32_e32 v63, v59
	v_pk_add_f32 v[58:59], v[102:103], 1.0 op_sel_hi:[1,0]
	v_pk_add_f32 v[56:57], v[80:81], v[76:77]
	v_div_scale_f32 v64, s[4:5], v59, v59, v9
	v_rcp_f32_e32 v65, v64
	v_pk_add_f32 v[52:53], v[60:61], v[62:63]
	v_exp_f32_e32 v92, v92
	v_pk_add_f32 v[52:53], v[56:57], v[52:53]
	v_exp_f32_e32 v93, v93
	v_pk_add_f32 v[52:53], v[52:53], v[52:53] op_sel:[0,1] op_sel_hi:[1,0]
	v_pk_mul_f32 v[2:3], v[90:91], v[2:3] op_sel_hi:[0,1]
	v_fma_f32 v53, -v64, v65, 1.0
	v_fmac_f32_e32 v65, v53, v65
	v_div_scale_f32 v53, vcc, v9, v59, v9
	v_mul_f32_e32 v56, v53, v65
	v_fma_f32 v57, -v64, v56, v53
	v_fmac_f32_e32 v56, v57, v65
	v_div_scale_f32 v57, s[4:5], v58, v58, v8
	v_rcp_f32_e32 v60, v57
	v_fma_f32 v53, -v64, v56, v53
	v_div_fmas_f32 v53, v53, v65, v56
	v_div_fixup_f32 v9, v53, v59, v9
	v_fma_f32 v53, -v57, v60, 1.0
	v_fmac_f32_e32 v60, v53, v60
	v_div_scale_f32 v53, vcc, v8, v58, v8
	v_mul_f32_e32 v56, v53, v60
	v_fma_f32 v59, -v57, v56, v53
	v_fmac_f32_e32 v56, v59, v60
	v_fma_f32 v53, -v57, v56, v53
	v_div_scale_f32 v57, s[4:5], v55, v55, v11
	v_rcp_f32_e32 v59, v57
	v_div_fmas_f32 v53, v53, v60, v56
	v_div_fixup_f32 v8, v53, v58, v8
	v_pk_add_f32 v[8:9], v[44:45], v[8:9]
	v_fma_f32 v44, -v57, v59, 1.0
	v_fmac_f32_e32 v59, v44, v59
	v_div_scale_f32 v44, vcc, v11, v55, v11
	v_mul_f32_e32 v45, v44, v59
	v_fma_f32 v53, -v57, v45, v44
	v_fmac_f32_e32 v45, v53, v59
	v_div_scale_f32 v53, s[4:5], v54, v54, v10
	v_rcp_f32_e32 v56, v53
	v_fma_f32 v44, -v57, v45, v44
	v_div_fmas_f32 v44, v44, v59, v45
	v_div_fixup_f32 v11, v44, v55, v11
	v_fma_f32 v44, -v53, v56, 1.0
	v_fmac_f32_e32 v56, v44, v56
	v_div_scale_f32 v44, vcc, v10, v54, v10
	v_mul_f32_e32 v45, v44, v56
	v_fma_f32 v55, -v53, v45, v44
	v_fmac_f32_e32 v45, v55, v56
	v_fma_f32 v44, -v53, v45, v44
	v_div_fmas_f32 v44, v44, v56, v45
	v_div_fixup_f32 v10, v44, v54, v10
	v_pk_add_f32 v[10:11], v[46:47], v[10:11]
	v_div_scale_f32 v53, s[4:5], v41, v41, v5
	v_mov_b32_e32 v46, v9
	v_mov_b32_e32 v47, v11
	v_rcp_f32_e32 v54, v53
	v_mov_b32_e32 v44, v8
	v_mov_b32_e32 v45, v10
	v_pk_mul_f32 v[46:47], v[46:47], v[46:47]
	v_pk_mul_f32 v[2:3], v[26:27], v[2:3]
	v_pk_fma_f32 v[44:45], v[44:45], v[44:45], v[46:47]
	v_pk_add_f32 v[26:27], v[92:93], 1.0 op_sel_hi:[1,0]
	v_pk_add_f32 v[44:45], v[44:45], v[44:45] op_sel:[0,1] op_sel_hi:[1,0]
	s_nop 0
	v_fma_f32 v45, -v53, v54, 1.0
	v_fmac_f32_e32 v54, v45, v54
	v_div_scale_f32 v45, vcc, v5, v41, v5
	v_mul_f32_e32 v46, v45, v54
	v_fma_f32 v47, -v53, v46, v45
	v_fmac_f32_e32 v46, v47, v54
	v_div_scale_f32 v47, s[4:5], v40, v40, v4
	v_fma_f32 v45, -v53, v46, v45
	v_rcp_f32_e32 v53, v47
	v_div_fmas_f32 v45, v45, v54, v46
	v_div_fixup_f32 v5, v45, v41, v5
	v_fma_f32 v41, -v47, v53, 1.0
	v_fmac_f32_e32 v53, v41, v53
	v_div_scale_f32 v41, vcc, v4, v40, v4
	v_mul_f32_e32 v45, v41, v53
	v_fma_f32 v46, -v47, v45, v41
	v_fmac_f32_e32 v45, v46, v53
	v_fma_f32 v41, -v47, v45, v41
	v_div_fmas_f32 v41, v41, v53, v45
	v_div_fixup_f32 v4, v41, v40, v4
	v_pk_add_f32 v[40:41], v[96:97], 1.0 op_sel_hi:[1,0]
	v_pk_add_f32 v[4:5], v[32:33], v[4:5]
	v_div_scale_f32 v42, s[4:5], v41, v41, v7
	v_rcp_f32_e32 v43, v42
	v_mul_f32_e32 v32, v5, v5
	v_pk_fma_f32 v[32:33], v[4:5], v[4:5], v[32:33] op_sel_hi:[1,1,0]
	s_nop 0
	v_fma_f32 v33, -v42, v43, 1.0
	v_fmac_f32_e32 v43, v33, v43
	v_div_scale_f32 v33, vcc, v7, v41, v7
	v_mul_f32_e32 v45, v33, v43
	v_fma_f32 v46, -v42, v45, v33
	v_fmac_f32_e32 v45, v46, v43
	v_fma_f32 v33, -v42, v45, v33
	v_div_scale_f32 v42, s[4:5], v40, v40, v6
	v_rcp_f32_e32 v46, v42
	v_div_fmas_f32 v33, v33, v43, v45
	v_div_fixup_f32 v7, v33, v41, v7
	v_fma_f32 v33, -v42, v46, 1.0
	v_fmac_f32_e32 v46, v33, v46
	v_div_scale_f32 v33, vcc, v6, v40, v6
	v_mul_f32_e32 v41, v33, v46
	v_fma_f32 v43, -v42, v41, v33
	v_fmac_f32_e32 v41, v43, v46
	v_fma_f32 v33, -v42, v41, v33
	v_div_fmas_f32 v33, v33, v46, v41
	v_div_fixup_f32 v6, v33, v40, v6
	v_div_scale_f32 v33, s[4:5], v25, v25, v1
	v_rcp_f32_e32 v40, v33
	v_pk_add_f32 v[6:7], v[34:35], v[6:7]
	s_nop 0
	v_mul_f32_e32 v34, v7, v7
	v_pk_fma_f32 v[34:35], v[6:7], v[6:7], v[34:35] op_sel_hi:[1,1,0]
	s_nop 0
	v_fma_f32 v35, -v33, v40, 1.0
	v_fmac_f32_e32 v40, v35, v40
	v_div_scale_f32 v35, vcc, v1, v25, v1
	v_mul_f32_e32 v41, v35, v40
	v_fma_f32 v42, -v33, v41, v35
	v_fmac_f32_e32 v41, v42, v40
	v_fma_f32 v33, -v33, v41, v35
	v_div_scale_f32 v35, s[4:5], v24, v24, v0
	v_rcp_f32_e32 v42, v35
	v_div_fmas_f32 v33, v33, v40, v41
	v_div_fixup_f32 v1, v33, v25, v1
	v_fma_f32 v25, -v35, v42, 1.0
	v_fmac_f32_e32 v42, v25, v42
	v_div_scale_f32 v25, vcc, v0, v24, v0
	v_mul_f32_e32 v33, v25, v42
	v_fma_f32 v40, -v35, v33, v25
	v_fmac_f32_e32 v33, v40, v42
	v_fma_f32 v25, -v35, v33, v25
	v_div_fmas_f32 v25, v25, v42, v33
	v_div_scale_f32 v33, s[4:5], v27, v27, v3
	v_rcp_f32_e32 v35, v33
	v_div_fixup_f32 v0, v25, v24, v0
	v_pk_add_f32 v[12:13], v[12:13], v[0:1]
	v_fma_f32 v24, -v33, v35, 1.0
	v_fmac_f32_e32 v35, v24, v35
	v_div_scale_f32 v24, vcc, v3, v27, v3
	v_mul_f32_e32 v25, v24, v35
	v_fma_f32 v40, -v33, v25, v24
	v_fmac_f32_e32 v25, v40, v35
	v_fma_f32 v24, -v33, v25, v24
	v_div_scale_f32 v33, s[4:5], v26, v26, v2
	v_rcp_f32_e32 v40, v33
	v_div_fmas_f32 v24, v24, v35, v25
	v_div_fixup_f32 v3, v24, v27, v3
	v_pk_mul_f32 v[0:1], v[12:13], v[12:13]
	v_fma_f32 v24, -v33, v40, 1.0
	v_fmac_f32_e32 v40, v24, v40
	v_div_scale_f32 v24, vcc, v2, v26, v2
	v_mul_f32_e32 v25, v24, v40
	v_fma_f32 v27, -v33, v25, v24
	v_fmac_f32_e32 v25, v27, v40
	v_fma_f32 v24, -v33, v25, v24
	v_div_fmas_f32 v24, v24, v40, v25
	v_div_fixup_f32 v2, v24, v26, v2
	v_pk_add_f32 v[14:15], v[14:15], v[2:3]
	v_mov_b32_e32 v53, v0
	v_pk_mul_f32 v[2:3], v[14:15], v[14:15]
	v_mov_b32_e32 v45, v1
	v_mov_b32_e32 v33, v2
	v_mov_b32_e32 v35, v3
	v_pk_add_f32 v[0:1], v[52:53], v[44:45]
	v_pk_add_f32 v[2:3], v[32:33], v[34:35]
	v_lshl_add_u64 v[24:25], s[0:1], 0, v[88:89]
	v_pk_add_f32 v[0:1], v[0:1], v[2:3]
	s_mov_b32 s0, 0x4001000
	v_add_f32_e32 v0, v0, v1
	ds_bpermute_b32 v1, v91, v0
	s_waitcnt lgkmcnt(0)
	v_add_f32_e32 v0, v0, v1
	ds_bpermute_b32 v1, v116, v0
	s_waitcnt lgkmcnt(0)
	v_add_f32_e32 v0, v0, v1
	ds_bpermute_b32 v1, v117, v0
	s_waitcnt lgkmcnt(0)
	v_add_f32_e32 v0, v0, v1
	ds_bpermute_b32 v1, v118, v0
	s_waitcnt lgkmcnt(0)
	v_add_f32_e32 v0, v0, v1
	ds_bpermute_b32 v1, v119, v0
	s_waitcnt lgkmcnt(0)
	v_add_f32_e32 v0, v0, v1
	ds_bpermute_b32 v1, v120, v0
	s_waitcnt lgkmcnt(0)
	v_add_f32_e32 v0, v0, v1
	v_fmac_f32_e32 v121, 0x3a000000, v0
	v_mul_f32_e32 v0, 0x4b800000, v121
	v_cmp_gt_f32_e32 vcc, s2, v121
	s_nop 1
	v_cndmask_b32_e32 v0, v121, v0, vcc
	v_rsq_f32_e32 v0, v0
	s_nop 0
	v_mul_f32_e32 v1, 0x45800000, v0
	v_cndmask_b32_e32 v26, v0, v1, vcc
	s_waitcnt vmcnt(0)
	v_pk_mul_f32 v[0:1], v[26:27], v[20:21] op_sel_hi:[0,1]
	v_pk_mul_f32 v[2:3], v[26:27], v[22:23] op_sel_hi:[0,1]
	v_add_co_u32_e32 v20, vcc, s0, v24
	v_pk_mul_f32 v[2:3], v[48:49], v[2:3]
	v_pk_mul_f32 v[0:1], v[68:69], v[0:1]
	v_addc_co_u32_e32 v21, vcc, 0, v25, vcc
	global_store_dwordx4 v[20:21], v[0:3], off offset:-4096
	s_nop 1
	s_mov_b64 s[0:1], 0x4000000
	v_lshl_add_u64 v[22:23], v[24:25], 0, s[0:1]
	v_lshl_add_u64 v[24:25], s[78:79], 0, v[88:89]
	v_pk_mul_f32 v[2:3], v[26:27], v[190:191] op_sel_hi:[0,1]
	v_pk_mul_f32 v[0:1], v[26:27], v[188:189] op_sel_hi:[0,1]
	v_pk_mul_f32 v[0:1], v[50:51], v[0:1]
	v_pk_mul_f32 v[2:3], v[70:71], v[2:3]
	global_store_dwordx4 v[22:23], v[0:3], off offset:1024
	s_nop 1
	v_pk_mul_f32 v[2:3], v[26:27], v[194:195] op_sel_hi:[0,1]
	v_pk_mul_f32 v[0:1], v[26:27], v[192:193] op_sel_hi:[0,1]
	v_pk_mul_f32 v[0:1], v[36:37], v[0:1]
	v_pk_mul_f32 v[2:3], v[38:39], v[2:3]
	global_store_dwordx4 v[22:23], v[0:3], off offset:2048
	s_nop 1
	v_pk_mul_f32 v[2:3], v[26:27], v[198:199] op_sel_hi:[0,1]
	v_pk_mul_f32 v[0:1], v[26:27], v[196:197] op_sel_hi:[0,1]
	v_pk_mul_f32 v[0:1], v[28:29], v[0:1]
	v_pk_mul_f32 v[2:3], v[16:17], v[2:3]
	v_add_co_u32_e32 v16, vcc, s3, v24
	global_store_dwordx4 v[22:23], v[0:3], off offset:3072
	s_nop 0
	v_addc_co_u32_e32 v17, vcc, 0, v25, vcc
	s_nop 1
	v_pk_mul_f32 v[2:3], v[26:27], v[202:203] op_sel_hi:[0,1]
	v_pk_mul_f32 v[0:1], v[26:27], v[200:201] op_sel_hi:[0,1]
	v_pk_mul_f32 v[0:1], v[18:19], v[0:1]
	v_pk_mul_f32 v[2:3], v[30:31], v[2:3]
	global_store_dwordx4 v[20:21], v[0:3], off
	s_nop 1
	v_pk_mul_f32 v[2:3], v[26:27], v[206:207] op_sel_hi:[0,1]
	v_pk_mul_f32 v[0:1], v[26:27], v[204:205] op_sel_hi:[0,1]
	v_pk_mul_f32 v[0:1], v[8:9], v[0:1]
	v_pk_mul_f32 v[2:3], v[10:11], v[2:3]
	global_store_dwordx4 v[20:21], v[0:3], off offset:1024
	s_nop 1
	v_pk_mul_f32 v[2:3], v[26:27], v[210:211] op_sel_hi:[0,1]
	v_pk_mul_f32 v[0:1], v[26:27], v[208:209] op_sel_hi:[0,1]
	v_pk_mul_f32 v[0:1], v[4:5], v[0:1]
	v_pk_mul_f32 v[2:3], v[6:7], v[2:3]
	global_store_dwordx4 v[20:21], v[0:3], off offset:2048
	s_nop 1
	v_pk_mul_f32 v[2:3], v[26:27], v[216:217] op_sel_hi:[0,1]
	v_pk_mul_f32 v[0:1], v[26:27], v[214:215] op_sel_hi:[0,1]
	v_pk_mul_f32 v[0:1], v[12:13], v[0:1]
	v_pk_mul_f32 v[2:3], v[14:15], v[2:3]
	global_store_dwordx4 v[20:21], v[0:3], off offset:3072
